# v11_m2_lru_chain_batched
# speedup vs baseline: 1.0316x; 1.0316x over previous
; __device__ __forceinline__ void mix_m2(const MixCtx& c) {
;     ...
;             for (int c0 = 0; c0 < NCH; c0 += 32) { float av[32], hv[32];
; #pragma unroll
;                 for (int i = 0; i < 32; ++i) { av[i] = A[(c0 + i) * 512]; hv[i] = H[(c0 + i) * 512]; }
; #pragma unroll
;                 for (int i = 0; i < 32; ++i) { HI[(c0 + i) * 512] = hh; hh = av[i] * hh + hv[i]; } } }
.LBB0_486:
	s_add_i32 s6, s6, 32
	s_mov_b64 s[20:21], 0x10000
	v_add_co_u32_e32 v6, vcc, 0xffdf0800, v0
	s_nop 1
	v_addc_co_u32_e32 v7, vcc, -1, v1, vcc
	v_add_co_u32_e32 v8, vcc, 0xffef0800, v0
	s_nop 1
	v_addc_co_u32_e32 v9, vcc, -1, v1, vcc
	v_add_co_u32_e32 v10, vcc, 0xffff0800, v0
	s_nop 1
	v_addc_co_u32_e32 v11, vcc, -1, v1, vcc
	v_mov_b32_e32 v12, 0x1000
	v_mov_b32_e32 v13, 0
	global_load_dword v34, v[6:7], off
	global_load_dword v35, v[6:7], off offset:2048
	global_load_dword v222, v[8:9], off
	global_load_dword v223, v[8:9], off offset:2048
	v_lshl_add_u64 v[6:7], v[6:7], 0, v[12:13]
	v_lshl_add_u64 v[8:9], v[8:9], 0, v[12:13]
	global_load_dword v36, v[6:7], off
	global_load_dword v37, v[6:7], off offset:2048
	global_load_dword v224, v[8:9], off
	global_load_dword v225, v[8:9], off offset:2048
	v_lshl_add_u64 v[6:7], v[6:7], 0, v[12:13]
	v_lshl_add_u64 v[8:9], v[8:9], 0, v[12:13]
	global_load_dword v38, v[6:7], off
	global_load_dword v39, v[6:7], off offset:2048
	global_load_dword v226, v[8:9], off
	global_load_dword v227, v[8:9], off offset:2048
	v_lshl_add_u64 v[6:7], v[6:7], 0, v[12:13]
	v_lshl_add_u64 v[8:9], v[8:9], 0, v[12:13]
	global_load_dword v40, v[6:7], off
	global_load_dword v41, v[6:7], off offset:2048
	global_load_dword v228, v[8:9], off
	global_load_dword v229, v[8:9], off offset:2048
	v_lshl_add_u64 v[6:7], v[6:7], 0, v[12:13]
	v_lshl_add_u64 v[8:9], v[8:9], 0, v[12:13]
	global_load_dword v42, v[6:7], off
	global_load_dword v43, v[6:7], off offset:2048
	global_load_dword v230, v[8:9], off
	global_load_dword v231, v[8:9], off offset:2048
	v_lshl_add_u64 v[6:7], v[6:7], 0, v[12:13]
	v_lshl_add_u64 v[8:9], v[8:9], 0, v[12:13]
	global_load_dword v44, v[6:7], off
	global_load_dword v45, v[6:7], off offset:2048
	global_load_dword v232, v[8:9], off
	global_load_dword v233, v[8:9], off offset:2048
	v_lshl_add_u64 v[6:7], v[6:7], 0, v[12:13]
	v_lshl_add_u64 v[8:9], v[8:9], 0, v[12:13]
	global_load_dword v46, v[6:7], off
	global_load_dword v47, v[6:7], off offset:2048
	global_load_dword v234, v[8:9], off
	global_load_dword v235, v[8:9], off offset:2048
	v_lshl_add_u64 v[6:7], v[6:7], 0, v[12:13]
	v_lshl_add_u64 v[8:9], v[8:9], 0, v[12:13]
	global_load_dword v48, v[6:7], off
	global_load_dword v49, v[6:7], off offset:2048
	global_load_dword v236, v[8:9], off
	global_load_dword v237, v[8:9], off offset:2048
	v_lshl_add_u64 v[6:7], v[6:7], 0, v[12:13]
	v_lshl_add_u64 v[8:9], v[8:9], 0, v[12:13]
	global_load_dword v50, v[6:7], off
	global_load_dword v51, v[6:7], off offset:2048
	global_load_dword v238, v[8:9], off
	global_load_dword v239, v[8:9], off offset:2048
	v_lshl_add_u64 v[6:7], v[6:7], 0, v[12:13]
	v_lshl_add_u64 v[8:9], v[8:9], 0, v[12:13]
	global_load_dword v52, v[6:7], off
	global_load_dword v53, v[6:7], off offset:2048
	global_load_dword v240, v[8:9], off
	global_load_dword v241, v[8:9], off offset:2048
	v_lshl_add_u64 v[6:7], v[6:7], 0, v[12:13]
	v_lshl_add_u64 v[8:9], v[8:9], 0, v[12:13]
	global_load_dword v54, v[6:7], off
	global_load_dword v55, v[6:7], off offset:2048
	global_load_dword v242, v[8:9], off
	global_load_dword v243, v[8:9], off offset:2048
	v_lshl_add_u64 v[6:7], v[6:7], 0, v[12:13]
	v_lshl_add_u64 v[8:9], v[8:9], 0, v[12:13]
	global_load_dword v56, v[6:7], off
	global_load_dword v57, v[6:7], off offset:2048
	global_load_dword v244, v[8:9], off
	global_load_dword v245, v[8:9], off offset:2048
	v_lshl_add_u64 v[6:7], v[6:7], 0, v[12:13]
	v_lshl_add_u64 v[8:9], v[8:9], 0, v[12:13]
	global_load_dword v58, v[6:7], off
	global_load_dword v59, v[6:7], off offset:2048
	global_load_dword v246, v[8:9], off
	global_load_dword v247, v[8:9], off offset:2048
	v_lshl_add_u64 v[6:7], v[6:7], 0, v[12:13]
	v_lshl_add_u64 v[8:9], v[8:9], 0, v[12:13]
	global_load_dword v60, v[6:7], off
	global_load_dword v61, v[6:7], off offset:2048
	global_load_dword v248, v[8:9], off
	global_load_dword v249, v[8:9], off offset:2048
	v_lshl_add_u64 v[6:7], v[6:7], 0, v[12:13]
	v_lshl_add_u64 v[8:9], v[8:9], 0, v[12:13]
	global_load_dword v62, v[6:7], off
	global_load_dword v63, v[6:7], off offset:2048
	global_load_dword v250, v[8:9], off
	global_load_dword v251, v[8:9], off offset:2048
	v_lshl_add_u64 v[6:7], v[6:7], 0, v[12:13]
	v_lshl_add_u64 v[8:9], v[8:9], 0, v[12:13]
	global_load_dword v64, v[6:7], off
	global_load_dword v65, v[6:7], off offset:2048
	global_load_dword v252, v[8:9], off
	global_load_dword v253, v[8:9], off offset:2048
	s_waitcnt vmcnt(0)
; __device__ __forceinline__ void mix_m2(const MixCtx& c) {
;     ...
;             for (int c0 = 0; c0 < NCH; c0 += 32) { float av[32], hv[32];
; #pragma unroll
;                 for (int i = 0; i < 32; ++i) { av[i] = A[(c0 + i) * 512]; hv[i] = H[(c0 + i) * 512]; }
; #pragma unroll
;                 for (int i = 0; i < 32; ++i) { HI[(c0 + i) * 512] = hh; hh = av[i] * hh + hv[i]; } } }
	global_store_dword v[10:11], v31, off
	v_fmac_f32_e32 v222, v31, v34
	global_store_dword v[10:11], v222, off offset:2048
	v_fmac_f32_e32 v223, v222, v35
	v_lshl_add_u64 v[10:11], v[10:11], 0, v[12:13]
	global_store_dword v[10:11], v223, off
	v_fmac_f32_e32 v224, v223, v36
	global_store_dword v[10:11], v224, off offset:2048
	v_fmac_f32_e32 v225, v224, v37
	v_lshl_add_u64 v[10:11], v[10:11], 0, v[12:13]
	global_store_dword v[10:11], v225, off
	v_fmac_f32_e32 v226, v225, v38
	global_store_dword v[10:11], v226, off offset:2048
	v_fmac_f32_e32 v227, v226, v39
	v_lshl_add_u64 v[10:11], v[10:11], 0, v[12:13]
	global_store_dword v[10:11], v227, off
	v_fmac_f32_e32 v228, v227, v40
	global_store_dword v[10:11], v228, off offset:2048
	v_fmac_f32_e32 v229, v228, v41
	v_lshl_add_u64 v[10:11], v[10:11], 0, v[12:13]
	global_store_dword v[10:11], v229, off
	v_fmac_f32_e32 v230, v229, v42
	global_store_dword v[10:11], v230, off offset:2048
	v_fmac_f32_e32 v231, v230, v43
	v_lshl_add_u64 v[10:11], v[10:11], 0, v[12:13]
	global_store_dword v[10:11], v231, off
	v_fmac_f32_e32 v232, v231, v44
	global_store_dword v[10:11], v232, off offset:2048
	v_fmac_f32_e32 v233, v232, v45
	v_lshl_add_u64 v[10:11], v[10:11], 0, v[12:13]
	global_store_dword v[10:11], v233, off
	v_fmac_f32_e32 v234, v233, v46
	global_store_dword v[10:11], v234, off offset:2048
	v_fmac_f32_e32 v235, v234, v47
	v_lshl_add_u64 v[10:11], v[10:11], 0, v[12:13]
	global_store_dword v[10:11], v235, off
	v_fmac_f32_e32 v236, v235, v48
	global_store_dword v[10:11], v236, off offset:2048
	v_fmac_f32_e32 v237, v236, v49
	v_lshl_add_u64 v[10:11], v[10:11], 0, v[12:13]
	global_store_dword v[10:11], v237, off
	v_fmac_f32_e32 v238, v237, v50
	global_store_dword v[10:11], v238, off offset:2048
	v_fmac_f32_e32 v239, v238, v51
	v_lshl_add_u64 v[10:11], v[10:11], 0, v[12:13]
	global_store_dword v[10:11], v239, off
	v_fmac_f32_e32 v240, v239, v52
	global_store_dword v[10:11], v240, off offset:2048
	v_fmac_f32_e32 v241, v240, v53
	v_lshl_add_u64 v[10:11], v[10:11], 0, v[12:13]
	global_store_dword v[10:11], v241, off
	v_fmac_f32_e32 v242, v241, v54
	global_store_dword v[10:11], v242, off offset:2048
	v_fmac_f32_e32 v243, v242, v55
	v_lshl_add_u64 v[10:11], v[10:11], 0, v[12:13]
	global_store_dword v[10:11], v243, off
	v_fmac_f32_e32 v244, v243, v56
	global_store_dword v[10:11], v244, off offset:2048
	v_fmac_f32_e32 v245, v244, v57
	v_lshl_add_u64 v[10:11], v[10:11], 0, v[12:13]
	global_store_dword v[10:11], v245, off
	v_fmac_f32_e32 v246, v245, v58
	global_store_dword v[10:11], v246, off offset:2048
	v_fmac_f32_e32 v247, v246, v59
	v_lshl_add_u64 v[10:11], v[10:11], 0, v[12:13]
	global_store_dword v[10:11], v247, off
	v_fmac_f32_e32 v248, v247, v60
	global_store_dword v[10:11], v248, off offset:2048
	v_fmac_f32_e32 v249, v248, v61
	v_lshl_add_u64 v[10:11], v[10:11], 0, v[12:13]
	global_store_dword v[10:11], v249, off
	v_fmac_f32_e32 v250, v249, v62
	global_store_dword v[10:11], v250, off offset:2048
	v_fmac_f32_e32 v251, v250, v63
	v_lshl_add_u64 v[10:11], v[10:11], 0, v[12:13]
	global_store_dword v[10:11], v251, off
	v_fmac_f32_e32 v252, v251, v64
	global_store_dword v[10:11], v252, off offset:2048
	v_fmac_f32_e32 v253, v252, v65
	v_mov_b32_e32 v31, v253
	v_lshl_add_u64 v[0:1], v[0:1], 0, s[20:21]
	s_cmpk_gt_u32 s6, 0x5f
	s_cbranch_scc0 .LBB0_486
	v_add_u32_e32 v2, s3, v2
	s_movk_i32 s6, 0x7ff
	v_cmp_lt_i32_e32 vcc, s6, v2
	s_or_b64 s[34:35], vcc, s[34:35]
	v_add_u16_e32 v4, s3, v4
	s_andn2_b64 exec, exec, s[34:35]
	s_cbranch_execnz .LBB0_485
